# sample cross-attention: both K batches requested up front (second register bank), first V batch requested before the second K batch is consumed
# baseline (speedup 1.0000x reference)
.LBB11_2191:
	s_ashr_i32 s0, s71, 2
	s_add_i32 s10, s0, 0x4000
	s_ashr_i32 s11, s10, 31
	s_lshl_b64 s[88:89], s[10:11], 10
	s_lshl_b64 s[10:11], s[10:11], 11
	s_add_u32 s1, s6, s10
	s_addc_u32 s11, s7, s11
	s_lshl_b32 s10, s71, 8
	s_and_b32 s68, s10, 0x300
	s_lshl_b32 s10, s68, 1
	s_add_u32 s10, s1, s10
	s_addc_u32 s11, s11, 0
	v_lshl_add_u64 v[176:177], v[100:101], 1, s[10:11]
	s_barrier
	global_load_dwordx2 v[176:177], v[176:177], off
	s_ashr_i32 s1, s0, 31
	s_lshl_b64 s[0:1], s[0:1], 18
	s_add_u32 s0, s0, s70
	s_addc_u32 s1, s1, 0
	s_lshl_b64 s[90:91], s[0:1], 2
	s_add_u32 s0, s56, s90
	s_addc_u32 s1, s57, s91
	s_lshl_b32 s10, s68, 2
	s_add_u32 s0, s0, s10
	s_addc_u32 s1, s1, 0
	v_lshl_add_u64 v[62:63], v[100:101], 2, s[0:1]
	s_mov_b32 s0, 0
	s_lshl_b32 s1, s0, 4
	s_or_b32 s60, s1, s76
	s_lshl_b64 s[48:49], s[60:61], 12
	s_waitcnt lgkmcnt(0)
	v_lshl_add_u64 v[2:3], v[62:63], 0, s[48:49]
	s_or_b32 s48, s60, 1
	s_mov_b32 s49, s61
	s_lshl_b64 s[48:49], s[48:49], 12
	v_lshl_add_u64 v[4:5], v[62:63], 0, s[48:49]
	global_load_dwordx4 v[68:71], v[2:3], off nt
	global_load_dwordx4 v[58:61], v[4:5], off nt
	s_or_b32 s48, s60, 2
	s_mov_b32 s49, s61
	s_lshl_b64 s[48:49], s[48:49], 12
	v_lshl_add_u64 v[2:3], v[62:63], 0, s[48:49]
	s_or_b32 s48, s60, 3
	s_mov_b32 s49, s61
	s_lshl_b64 s[48:49], s[48:49], 12
	v_lshl_add_u64 v[4:5], v[62:63], 0, s[48:49]
	s_or_b32 s48, s60, 4
	s_mov_b32 s49, s61
	s_lshl_b64 s[48:49], s[48:49], 12
	global_load_dwordx4 v[54:57], v[2:3], off nt
	global_load_dwordx4 v[50:53], v[4:5], off nt
	v_lshl_add_u64 v[2:3], v[62:63], 0, s[48:49]
	s_or_b32 s48, s60, 5
	s_mov_b32 s49, s61
	s_lshl_b64 s[48:49], s[48:49], 12
	v_lshl_add_u64 v[4:5], v[62:63], 0, s[48:49]
	s_or_b32 s48, s60, 6
	s_mov_b32 s49, s61
	s_lshl_b64 s[48:49], s[48:49], 12
	global_load_dwordx4 v[46:49], v[2:3], off nt
	global_load_dwordx4 v[42:45], v[4:5], off nt
	v_lshl_add_u64 v[2:3], v[62:63], 0, s[48:49]
	s_or_b32 s48, s60, 7
	s_mov_b32 s49, s61
	s_lshl_b64 s[48:49], s[48:49], 12
	v_lshl_add_u64 v[4:5], v[62:63], 0, s[48:49]
	s_or_b32 s48, s60, 8
	s_mov_b32 s49, s61
	s_lshl_b64 s[48:49], s[48:49], 12
	global_load_dwordx4 v[38:41], v[2:3], off nt
	global_load_dwordx4 v[34:37], v[4:5], off nt
	v_lshl_add_u64 v[2:3], v[62:63], 0, s[48:49]
	s_or_b32 s48, s60, 9
	s_mov_b32 s49, s61
	s_lshl_b64 s[48:49], s[48:49], 12
	v_lshl_add_u64 v[4:5], v[62:63], 0, s[48:49]
	s_or_b32 s48, s60, 10
	s_mov_b32 s49, s61
	s_lshl_b64 s[48:49], s[48:49], 12
	global_load_dwordx4 v[30:33], v[2:3], off nt
	global_load_dwordx4 v[26:29], v[4:5], off nt
	v_lshl_add_u64 v[2:3], v[62:63], 0, s[48:49]
	s_or_b32 s48, s60, 11
	s_mov_b32 s49, s61
	s_lshl_b64 s[48:49], s[48:49], 12
	v_lshl_add_u64 v[4:5], v[62:63], 0, s[48:49]
	s_or_b32 s48, s60, 12
	s_mov_b32 s49, s61
	s_lshl_b64 s[48:49], s[48:49], 12
	global_load_dwordx4 v[22:25], v[2:3], off nt
	global_load_dwordx4 v[18:21], v[4:5], off nt
	v_lshl_add_u64 v[2:3], v[62:63], 0, s[48:49]
	s_or_b32 s48, s60, 13
	s_mov_b32 s49, s61
	s_lshl_b64 s[48:49], s[48:49], 12
	v_lshl_add_u64 v[4:5], v[62:63], 0, s[48:49]
	s_or_b32 s48, s60, 14
	s_mov_b32 s49, s61
	s_lshl_b64 s[48:49], s[48:49], 12
	s_or_b32 s60, s60, 15
	global_load_dwordx4 v[14:17], v[2:3], off nt
	global_load_dwordx4 v[10:13], v[4:5], off nt
	v_lshl_add_u64 v[2:3], v[62:63], 0, s[48:49]
	s_lshl_b64 s[48:49], s[60:61], 12
	v_lshl_add_u64 v[4:5], v[62:63], 0, s[48:49]
	global_load_dwordx4 v[6:9], v[2:3], off nt
	s_nop 0
	global_load_dwordx4 v[2:5], v[4:5], off nt
	s_mov_b32 s0, 1
	s_lshl_b32 s1, s0, 4
	s_or_b32 s60, s1, s76
	s_lshl_b64 s[48:49], s[60:61], 12
	s_waitcnt lgkmcnt(0)
	v_lshl_add_u64 v[166:167], v[62:63], 0, s[48:49]
	s_or_b32 s48, s60, 1
	s_mov_b32 s49, s61
	s_lshl_b64 s[48:49], s[48:49], 12
	v_lshl_add_u64 v[168:169], v[62:63], 0, s[48:49]
	global_load_dwordx4 v[106:109], v[166:167], off nt
	global_load_dwordx4 v[110:113], v[168:169], off nt
	s_or_b32 s48, s60, 2
	s_mov_b32 s49, s61
	s_lshl_b64 s[48:49], s[48:49], 12
	v_lshl_add_u64 v[166:167], v[62:63], 0, s[48:49]
	s_or_b32 s48, s60, 3
	s_mov_b32 s49, s61
	s_lshl_b64 s[48:49], s[48:49], 12
	v_lshl_add_u64 v[168:169], v[62:63], 0, s[48:49]
	s_or_b32 s48, s60, 4
	s_mov_b32 s49, s61
	s_lshl_b64 s[48:49], s[48:49], 12
	global_load_dwordx4 v[114:117], v[166:167], off nt
	global_load_dwordx4 v[118:121], v[168:169], off nt
	v_lshl_add_u64 v[166:167], v[62:63], 0, s[48:49]
	s_or_b32 s48, s60, 5
	s_mov_b32 s49, s61
	s_lshl_b64 s[48:49], s[48:49], 12
	v_lshl_add_u64 v[168:169], v[62:63], 0, s[48:49]
	s_or_b32 s48, s60, 6
	s_mov_b32 s49, s61
	s_lshl_b64 s[48:49], s[48:49], 12
	global_load_dwordx4 v[122:125], v[166:167], off nt
	global_load_dwordx4 v[126:129], v[168:169], off nt
	v_lshl_add_u64 v[166:167], v[62:63], 0, s[48:49]
	s_or_b32 s48, s60, 7
	s_mov_b32 s49, s61
	s_lshl_b64 s[48:49], s[48:49], 12
	v_lshl_add_u64 v[168:169], v[62:63], 0, s[48:49]
	s_or_b32 s48, s60, 8
	s_mov_b32 s49, s61
	s_lshl_b64 s[48:49], s[48:49], 12
	global_load_dwordx4 v[130:133], v[166:167], off nt
	global_load_dwordx4 v[134:137], v[168:169], off nt
	v_lshl_add_u64 v[166:167], v[62:63], 0, s[48:49]
	s_or_b32 s48, s60, 9
	s_mov_b32 s49, s61
	s_lshl_b64 s[48:49], s[48:49], 12
	v_lshl_add_u64 v[168:169], v[62:63], 0, s[48:49]
	s_or_b32 s48, s60, 10
	s_mov_b32 s49, s61
	s_lshl_b64 s[48:49], s[48:49], 12
	global_load_dwordx4 v[138:141], v[166:167], off nt
	global_load_dwordx4 v[142:145], v[168:169], off nt
	v_lshl_add_u64 v[166:167], v[62:63], 0, s[48:49]
	s_or_b32 s48, s60, 11
	s_mov_b32 s49, s61
	s_lshl_b64 s[48:49], s[48:49], 12
	v_lshl_add_u64 v[168:169], v[62:63], 0, s[48:49]
	s_or_b32 s48, s60, 12
	s_mov_b32 s49, s61
	s_lshl_b64 s[48:49], s[48:49], 12
	global_load_dwordx4 v[146:149], v[166:167], off nt
	global_load_dwordx4 v[150:153], v[168:169], off nt
	v_lshl_add_u64 v[166:167], v[62:63], 0, s[48:49]
	s_or_b32 s48, s60, 13
	s_mov_b32 s49, s61
	s_lshl_b64 s[48:49], s[48:49], 12
	v_lshl_add_u64 v[168:169], v[62:63], 0, s[48:49]
	s_or_b32 s48, s60, 14
	s_mov_b32 s49, s61
	s_lshl_b64 s[48:49], s[48:49], 12
	s_or_b32 s60, s60, 15
	global_load_dwordx4 v[154:157], v[166:167], off nt
	global_load_dwordx4 v[158:161], v[168:169], off nt
	v_lshl_add_u64 v[166:167], v[62:63], 0, s[48:49]
	s_lshl_b64 s[48:49], s[60:61], 12
	v_lshl_add_u64 v[168:169], v[62:63], 0, s[48:49]
	global_load_dwordx4 v[162:165], v[166:167], off nt
	s_nop 0
	global_load_dwordx4 v[166:169], v[168:169], off nt
	s_waitcnt vmcnt(32)
	v_lshlrev_b32_e32 v64, 16, v176
	v_and_b32_e32 v65, 0xffff0000, v176
	v_lshlrev_b32_e32 v66, 16, v177
	v_and_b32_e32 v67, 0xffff0000, v177
	s_waitcnt vmcnt(31)
	v_mul_f32_e32 v69, v69, v65
	v_mul_f32_e32 v71, v71, v67
	v_fmac_f32_e32 v69, v68, v64
	v_fmac_f32_e32 v71, v70, v66
	v_add_f32_e32 v68, v69, v71
	s_waitcnt vmcnt(30)
	v_mul_f32_e32 v59, v59, v65
	v_fmac_f32_e32 v59, v58, v64
	v_mul_f32_e32 v58, v61, v67
	v_fmac_f32_e32 v58, v60, v66
	v_add_f32_e32 v58, v59, v58
	s_waitcnt vmcnt(29)
	v_mul_f32_e32 v55, v55, v65
	v_fmac_f32_e32 v55, v54, v64
	v_mul_f32_e32 v54, v57, v67
	v_fmac_f32_e32 v54, v56, v66
	v_add_f32_e32 v54, v55, v54
	s_waitcnt vmcnt(28)
	v_mul_f32_e32 v51, v51, v65
	v_fmac_f32_e32 v51, v50, v64
	v_mul_f32_e32 v50, v53, v67
	v_fmac_f32_e32 v50, v52, v66
	v_add_f32_e32 v50, v51, v50
	s_waitcnt vmcnt(27)
	v_mul_f32_e32 v47, v47, v65
	v_fmac_f32_e32 v47, v46, v64
	v_mul_f32_e32 v46, v49, v67
	v_fmac_f32_e32 v46, v48, v66
	v_add_f32_e32 v46, v47, v46
	s_waitcnt vmcnt(26)
	v_mul_f32_e32 v43, v43, v65
	v_fmac_f32_e32 v43, v42, v64
	v_mul_f32_e32 v42, v45, v67
	v_fmac_f32_e32 v42, v44, v66
	v_add_f32_e32 v42, v43, v42
	s_waitcnt vmcnt(25)
	v_mul_f32_e32 v39, v39, v65
	v_fmac_f32_e32 v39, v38, v64
	v_mul_f32_e32 v38, v41, v67
	v_fmac_f32_e32 v38, v40, v66
	v_add_f32_e32 v38, v39, v38
	s_waitcnt vmcnt(24)
	v_mul_f32_e32 v35, v35, v65
	v_fmac_f32_e32 v35, v34, v64
	v_mul_f32_e32 v34, v37, v67
	v_fmac_f32_e32 v34, v36, v66
	v_add_f32_e32 v34, v35, v34
	s_waitcnt vmcnt(23)
	v_mul_f32_e32 v31, v31, v65
	v_fmac_f32_e32 v31, v30, v64
	v_mul_f32_e32 v30, v33, v67
	v_fmac_f32_e32 v30, v32, v66
	v_add_f32_e32 v30, v31, v30
	s_waitcnt vmcnt(22)
	v_mul_f32_e32 v27, v27, v65
	v_fmac_f32_e32 v27, v26, v64
	v_mul_f32_e32 v26, v29, v67
	v_fmac_f32_e32 v26, v28, v66
	v_add_f32_e32 v26, v27, v26
	s_waitcnt vmcnt(21)
	v_mul_f32_e32 v23, v23, v65
	v_fmac_f32_e32 v23, v22, v64
	v_mul_f32_e32 v22, v25, v67
	v_fmac_f32_e32 v22, v24, v66
	v_add_f32_e32 v22, v23, v22
	s_waitcnt vmcnt(20)
	v_mul_f32_e32 v19, v19, v65
	v_fmac_f32_e32 v19, v18, v64
	v_mul_f32_e32 v18, v21, v67
	v_fmac_f32_e32 v18, v20, v66
	v_add_f32_e32 v18, v19, v18
	s_waitcnt vmcnt(19)
	v_mul_f32_e32 v15, v15, v65
	v_fmac_f32_e32 v15, v14, v64
	v_mul_f32_e32 v14, v17, v67
	v_fmac_f32_e32 v14, v16, v66
	v_add_f32_e32 v14, v15, v14
	s_waitcnt vmcnt(18)
	v_mul_f32_e32 v11, v11, v65
	v_fmac_f32_e32 v11, v10, v64
	v_mul_f32_e32 v10, v13, v67
	v_fmac_f32_e32 v10, v12, v66
	v_add_f32_e32 v10, v11, v10
	s_waitcnt vmcnt(17)
	v_mul_f32_e32 v7, v7, v65
	v_fmac_f32_e32 v7, v6, v64
	v_mul_f32_e32 v6, v9, v67
	v_fmac_f32_e32 v6, v8, v66
	v_add_f32_e32 v6, v7, v6
	s_waitcnt vmcnt(16)
	v_mul_f32_e32 v3, v3, v65
	v_fmac_f32_e32 v3, v2, v64
	v_mul_f32_e32 v2, v5, v67
	v_fmac_f32_e32 v2, v4, v66
	v_add_f32_e32 v2, v3, v2
	ds_bpermute_b32 v69, v200, v68
	ds_bpermute_b32 v59, v200, v58
	ds_bpermute_b32 v55, v200, v54
	ds_bpermute_b32 v51, v200, v50
	ds_bpermute_b32 v47, v200, v46
	ds_bpermute_b32 v43, v200, v42
	ds_bpermute_b32 v39, v200, v38
	ds_bpermute_b32 v35, v200, v34
	s_waitcnt lgkmcnt(7)
	v_add_f32_e32 v68, v68, v69
	s_waitcnt lgkmcnt(6)
	v_add_f32_e32 v58, v58, v59
	s_waitcnt lgkmcnt(5)
	v_add_f32_e32 v54, v54, v55
	s_waitcnt lgkmcnt(4)
	v_add_f32_e32 v50, v50, v51
	s_waitcnt lgkmcnt(3)
	v_add_f32_e32 v46, v46, v47
	s_waitcnt lgkmcnt(2)
	v_add_f32_e32 v42, v42, v43
	s_waitcnt lgkmcnt(1)
	v_add_f32_e32 v38, v38, v39
	s_waitcnt lgkmcnt(0)
	v_add_f32_e32 v34, v34, v35
	ds_bpermute_b32 v69, v201, v68
	ds_bpermute_b32 v59, v201, v58
	ds_bpermute_b32 v55, v201, v54
	ds_bpermute_b32 v51, v201, v50
	ds_bpermute_b32 v47, v201, v46
	ds_bpermute_b32 v43, v201, v42
	ds_bpermute_b32 v39, v201, v38
	ds_bpermute_b32 v35, v201, v34
	s_waitcnt lgkmcnt(7)
	v_add_f32_e32 v68, v68, v69
	s_waitcnt lgkmcnt(6)
	v_add_f32_e32 v58, v58, v59
	s_waitcnt lgkmcnt(5)
	v_add_f32_e32 v54, v54, v55
	s_waitcnt lgkmcnt(4)
	v_add_f32_e32 v50, v50, v51
	s_waitcnt lgkmcnt(3)
	v_add_f32_e32 v46, v46, v47
	s_waitcnt lgkmcnt(2)
	v_add_f32_e32 v42, v42, v43
	s_waitcnt lgkmcnt(1)
	v_add_f32_e32 v38, v38, v39
	s_waitcnt lgkmcnt(0)
	v_add_f32_e32 v34, v34, v35
	ds_bpermute_b32 v69, v202, v68
	ds_bpermute_b32 v59, v202, v58
	ds_bpermute_b32 v55, v202, v54
	ds_bpermute_b32 v51, v202, v50
	ds_bpermute_b32 v47, v202, v46
	ds_bpermute_b32 v43, v202, v42
	ds_bpermute_b32 v39, v202, v38
	ds_bpermute_b32 v35, v202, v34
	s_waitcnt lgkmcnt(7)
	v_add_f32_e32 v68, v68, v69
	s_waitcnt lgkmcnt(6)
	v_add_f32_e32 v58, v58, v59
	s_waitcnt lgkmcnt(5)
	v_add_f32_e32 v54, v54, v55
	s_waitcnt lgkmcnt(4)
	v_add_f32_e32 v50, v50, v51
	s_waitcnt lgkmcnt(3)
	v_add_f32_e32 v46, v46, v47
	s_waitcnt lgkmcnt(2)
	v_add_f32_e32 v42, v42, v43
	s_waitcnt lgkmcnt(1)
	v_add_f32_e32 v38, v38, v39
	s_waitcnt lgkmcnt(0)
	v_add_f32_e32 v34, v34, v35
	ds_bpermute_b32 v69, v203, v68
	ds_bpermute_b32 v59, v203, v58
	ds_bpermute_b32 v55, v203, v54
	ds_bpermute_b32 v51, v203, v50
	ds_bpermute_b32 v47, v203, v46
	ds_bpermute_b32 v43, v203, v42
	ds_bpermute_b32 v39, v203, v38
	ds_bpermute_b32 v35, v203, v34
	s_waitcnt lgkmcnt(7)
	v_add_f32_e32 v68, v68, v69
	s_waitcnt lgkmcnt(6)
	v_add_f32_e32 v58, v58, v59
	s_waitcnt lgkmcnt(5)
	v_add_f32_e32 v54, v54, v55
	s_waitcnt lgkmcnt(4)
	v_add_f32_e32 v50, v50, v51
	s_waitcnt lgkmcnt(3)
	v_add_f32_e32 v46, v46, v47
	s_waitcnt lgkmcnt(2)
	v_add_f32_e32 v42, v42, v43
	s_waitcnt lgkmcnt(1)
	v_add_f32_e32 v38, v38, v39
	s_waitcnt lgkmcnt(0)
	v_add_f32_e32 v34, v34, v35
	ds_bpermute_b32 v69, v204, v68
	ds_bpermute_b32 v59, v204, v58
	ds_bpermute_b32 v55, v204, v54
	ds_bpermute_b32 v51, v204, v50
	ds_bpermute_b32 v47, v204, v46
	ds_bpermute_b32 v43, v204, v42
	ds_bpermute_b32 v39, v204, v38
	ds_bpermute_b32 v35, v204, v34
	s_waitcnt lgkmcnt(7)
	v_add_f32_e32 v68, v68, v69
	s_waitcnt lgkmcnt(6)
	v_add_f32_e32 v58, v58, v59
	s_waitcnt lgkmcnt(5)
	v_add_f32_e32 v54, v54, v55
	s_waitcnt lgkmcnt(4)
	v_add_f32_e32 v50, v50, v51
	s_waitcnt lgkmcnt(3)
	v_add_f32_e32 v46, v46, v47
	s_waitcnt lgkmcnt(2)
	v_add_f32_e32 v42, v42, v43
	s_waitcnt lgkmcnt(1)
	v_add_f32_e32 v38, v38, v39
	s_waitcnt lgkmcnt(0)
	v_add_f32_e32 v34, v34, v35
	ds_bpermute_b32 v69, v205, v68
	ds_bpermute_b32 v59, v205, v58
	ds_bpermute_b32 v55, v205, v54
	ds_bpermute_b32 v51, v205, v50
	ds_bpermute_b32 v47, v205, v46
	ds_bpermute_b32 v43, v205, v42
	ds_bpermute_b32 v39, v205, v38
	ds_bpermute_b32 v35, v205, v34
	s_waitcnt lgkmcnt(7)
	v_add_f32_e32 v68, v68, v69
	s_waitcnt lgkmcnt(6)
	v_add_f32_e32 v58, v58, v59
	s_waitcnt lgkmcnt(5)
	v_add_f32_e32 v54, v54, v55
	s_waitcnt lgkmcnt(4)
	v_add_f32_e32 v50, v50, v51
	s_waitcnt lgkmcnt(3)
	v_add_f32_e32 v46, v46, v47
	s_waitcnt lgkmcnt(2)
	v_add_f32_e32 v42, v42, v43
	s_waitcnt lgkmcnt(1)
	v_add_f32_e32 v38, v38, v39
	s_waitcnt lgkmcnt(0)
	v_add_f32_e32 v34, v34, v35
	ds_bpermute_b32 v31, v200, v30
	ds_bpermute_b32 v27, v200, v26
	ds_bpermute_b32 v23, v200, v22
	ds_bpermute_b32 v19, v200, v18
	ds_bpermute_b32 v15, v200, v14
	ds_bpermute_b32 v11, v200, v10
	ds_bpermute_b32 v7, v200, v6
	ds_bpermute_b32 v3, v200, v2
	s_waitcnt lgkmcnt(7)
	v_add_f32_e32 v30, v30, v31
	s_waitcnt lgkmcnt(6)
	v_add_f32_e32 v26, v26, v27
	s_waitcnt lgkmcnt(5)
	v_add_f32_e32 v22, v22, v23
	s_waitcnt lgkmcnt(4)
	v_add_f32_e32 v18, v18, v19
	s_waitcnt lgkmcnt(3)
	v_add_f32_e32 v14, v14, v15
	s_waitcnt lgkmcnt(2)
	v_add_f32_e32 v10, v10, v11
	s_waitcnt lgkmcnt(1)
	v_add_f32_e32 v6, v6, v7
	s_waitcnt lgkmcnt(0)
	v_add_f32_e32 v2, v2, v3
	ds_bpermute_b32 v31, v201, v30
	ds_bpermute_b32 v27, v201, v26
	ds_bpermute_b32 v23, v201, v22
	ds_bpermute_b32 v19, v201, v18
	ds_bpermute_b32 v15, v201, v14
	ds_bpermute_b32 v11, v201, v10
	ds_bpermute_b32 v7, v201, v6
	ds_bpermute_b32 v3, v201, v2
	s_waitcnt lgkmcnt(7)
	v_add_f32_e32 v30, v30, v31
	s_waitcnt lgkmcnt(6)
	v_add_f32_e32 v26, v26, v27
	s_waitcnt lgkmcnt(5)
	v_add_f32_e32 v22, v22, v23
	s_waitcnt lgkmcnt(4)
	v_add_f32_e32 v18, v18, v19
	s_waitcnt lgkmcnt(3)
	v_add_f32_e32 v14, v14, v15
	s_waitcnt lgkmcnt(2)
	v_add_f32_e32 v10, v10, v11
	s_waitcnt lgkmcnt(1)
	v_add_f32_e32 v6, v6, v7
	s_waitcnt lgkmcnt(0)
	v_add_f32_e32 v2, v2, v3
	ds_bpermute_b32 v31, v202, v30
	ds_bpermute_b32 v27, v202, v26
	ds_bpermute_b32 v23, v202, v22
	ds_bpermute_b32 v19, v202, v18
	ds_bpermute_b32 v15, v202, v14
	ds_bpermute_b32 v11, v202, v10
	ds_bpermute_b32 v7, v202, v6
	ds_bpermute_b32 v3, v202, v2
	s_waitcnt lgkmcnt(7)
	v_add_f32_e32 v30, v30, v31
	s_waitcnt lgkmcnt(6)
	v_add_f32_e32 v26, v26, v27
	s_waitcnt lgkmcnt(5)
	v_add_f32_e32 v22, v22, v23
	s_waitcnt lgkmcnt(4)
	v_add_f32_e32 v18, v18, v19
	s_waitcnt lgkmcnt(3)
	v_add_f32_e32 v14, v14, v15
	s_waitcnt lgkmcnt(2)
	v_add_f32_e32 v10, v10, v11
	s_waitcnt lgkmcnt(1)
	v_add_f32_e32 v6, v6, v7
	s_waitcnt lgkmcnt(0)
	v_add_f32_e32 v2, v2, v3
	ds_bpermute_b32 v31, v203, v30
	ds_bpermute_b32 v27, v203, v26
	ds_bpermute_b32 v23, v203, v22
	ds_bpermute_b32 v19, v203, v18
	ds_bpermute_b32 v15, v203, v14
	ds_bpermute_b32 v11, v203, v10
	ds_bpermute_b32 v7, v203, v6
	ds_bpermute_b32 v3, v203, v2
	s_waitcnt lgkmcnt(7)
	v_add_f32_e32 v30, v30, v31
	s_waitcnt lgkmcnt(6)
	v_add_f32_e32 v26, v26, v27
	s_waitcnt lgkmcnt(5)
	v_add_f32_e32 v22, v22, v23
	s_waitcnt lgkmcnt(4)
	v_add_f32_e32 v18, v18, v19
	s_waitcnt lgkmcnt(3)
	v_add_f32_e32 v14, v14, v15
	s_waitcnt lgkmcnt(2)
	v_add_f32_e32 v10, v10, v11
	s_waitcnt lgkmcnt(1)
	v_add_f32_e32 v6, v6, v7
	s_waitcnt lgkmcnt(0)
	v_add_f32_e32 v2, v2, v3
	ds_bpermute_b32 v31, v204, v30
	ds_bpermute_b32 v27, v204, v26
	ds_bpermute_b32 v23, v204, v22
	ds_bpermute_b32 v19, v204, v18
	ds_bpermute_b32 v15, v204, v14
	ds_bpermute_b32 v11, v204, v10
	ds_bpermute_b32 v7, v204, v6
	ds_bpermute_b32 v3, v204, v2
	s_waitcnt lgkmcnt(7)
	v_add_f32_e32 v30, v30, v31
	s_waitcnt lgkmcnt(6)
	v_add_f32_e32 v26, v26, v27
	s_waitcnt lgkmcnt(5)
	v_add_f32_e32 v22, v22, v23
	s_waitcnt lgkmcnt(4)
	v_add_f32_e32 v18, v18, v19
	s_waitcnt lgkmcnt(3)
	v_add_f32_e32 v14, v14, v15
	s_waitcnt lgkmcnt(2)
	v_add_f32_e32 v10, v10, v11
	s_waitcnt lgkmcnt(1)
	v_add_f32_e32 v6, v6, v7
	s_waitcnt lgkmcnt(0)
	v_add_f32_e32 v2, v2, v3
	ds_bpermute_b32 v31, v205, v30
	ds_bpermute_b32 v27, v205, v26
	ds_bpermute_b32 v23, v205, v22
	ds_bpermute_b32 v19, v205, v18
	ds_bpermute_b32 v15, v205, v14
	ds_bpermute_b32 v11, v205, v10
	ds_bpermute_b32 v7, v205, v6
	ds_bpermute_b32 v3, v205, v2
	s_waitcnt lgkmcnt(7)
	v_add_f32_e32 v30, v30, v31
	s_waitcnt lgkmcnt(6)
	v_add_f32_e32 v26, v26, v27
	s_waitcnt lgkmcnt(5)
	v_add_f32_e32 v22, v22, v23
	s_waitcnt lgkmcnt(4)
	v_add_f32_e32 v18, v18, v19
	s_waitcnt lgkmcnt(3)
	v_add_f32_e32 v14, v14, v15
	s_waitcnt lgkmcnt(2)
	v_add_f32_e32 v10, v10, v11
	s_waitcnt lgkmcnt(1)
	v_add_f32_e32 v6, v6, v7
	s_waitcnt lgkmcnt(0)
	v_add_f32_e32 v2, v2, v3
	s_movk_i32 s60, 0x0
	s_add_i32 s0, s84, s60
	v_mov_b32_e32 v69, s0
	s_and_saveexec_b64 vcc, s[14:15]
	ds_write_b32 v69, v68
	s_or_b64 exec, exec, vcc
	s_and_saveexec_b64 vcc, s[16:17]
	ds_write_b32 v69, v58 offset:4
	s_or_b64 exec, exec, vcc
	s_and_saveexec_b64 vcc, s[18:19]
	ds_write_b32 v69, v54 offset:8
	s_or_b64 exec, exec, vcc
	s_and_saveexec_b64 vcc, s[20:21]
	ds_write_b32 v69, v50 offset:12
	s_or_b64 exec, exec, vcc
	s_and_saveexec_b64 vcc, s[22:23]
	ds_write_b32 v69, v46 offset:16
	s_or_b64 exec, exec, vcc
	s_and_saveexec_b64 vcc, s[24:25]
	ds_write_b32 v69, v42 offset:20
	s_or_b64 exec, exec, vcc
	s_and_saveexec_b64 vcc, s[26:27]
	ds_write_b32 v69, v38 offset:24
	s_or_b64 exec, exec, vcc
	s_and_saveexec_b64 vcc, s[28:29]
	ds_write_b32 v69, v34 offset:28
	s_or_b64 exec, exec, vcc
	s_and_saveexec_b64 vcc, s[30:31]
	ds_write_b32 v69, v30 offset:32
	s_or_b64 exec, exec, vcc
	s_and_saveexec_b64 vcc, s[34:35]
	ds_write_b32 v69, v26 offset:36
	s_or_b64 exec, exec, vcc
	s_and_saveexec_b64 vcc, s[36:37]
	ds_write_b32 v69, v22 offset:40
	s_or_b64 exec, exec, vcc
	s_and_saveexec_b64 vcc, s[38:39]
	ds_write_b32 v69, v18 offset:44
	s_or_b64 exec, exec, vcc
	s_and_saveexec_b64 vcc, s[40:41]
	ds_write_b32 v69, v14 offset:48
	s_or_b64 exec, exec, vcc
	s_and_saveexec_b64 vcc, s[42:43]
	ds_write_b32 v69, v10 offset:52
	s_or_b64 exec, exec, vcc
	s_and_saveexec_b64 vcc, s[44:45]
	ds_write_b32 v69, v6 offset:56
	s_or_b64 exec, exec, vcc
	s_and_saveexec_b64 vcc, s[46:47]
	ds_write_b32 v69, v2 offset:60
	s_or_b64 exec, exec, vcc
	s_add_u32 s0, s58, s90
	s_addc_u32 s1, s59, s91
	s_lshl_b32 s10, s68, 2
	s_add_u32 s0, s0, s10
	s_addc_u32 s1, s1, 0
	v_lshl_add_u64 v[174:175], v[100:101], 2, s[0:1]
	v_readlane_b32 s0, v243, 2
	v_readlane_b32 s1, v243, 3
	s_waitcnt lgkmcnt(0)
	v_lshl_add_u64 v[2:3], v[174:175], 0, s[0:1]
	v_readlane_b32 s0, v244, 4
	v_readlane_b32 s1, v244, 5
	s_nop 1
	v_lshl_add_u64 v[4:5], v[174:175], 0, s[0:1]
	v_readlane_b32 s0, v244, 6
	v_readlane_b32 s1, v244, 7
	global_load_dwordx4 v[170:173], v[2:3], off nt
	global_load_dwordx4 v[42:45], v[4:5], off nt
	v_lshl_add_u64 v[2:3], v[174:175], 0, s[0:1]
	v_readlane_b32 s0, v244, 8
	v_readlane_b32 s1, v244, 9
	s_nop 1
	v_lshl_add_u64 v[4:5], v[174:175], 0, s[0:1]
	v_readlane_b32 s0, v244, 10
	v_readlane_b32 s1, v244, 11
	global_load_dwordx4 v[58:61], v[2:3], off nt
	global_load_dwordx4 v[34:37], v[4:5], off nt
	v_lshl_add_u64 v[2:3], v[174:175], 0, s[0:1]
	v_readlane_b32 s0, v244, 12
	v_readlane_b32 s1, v244, 13
	s_nop 1
	v_lshl_add_u64 v[4:5], v[174:175], 0, s[0:1]
	v_readlane_b32 s0, v244, 14
	v_readlane_b32 s1, v244, 15
	global_load_dwordx4 v[54:57], v[2:3], off nt
	global_load_dwordx4 v[26:29], v[4:5], off nt
	v_lshl_add_u64 v[2:3], v[174:175], 0, s[0:1]
	v_readlane_b32 s0, v244, 16
	v_readlane_b32 s1, v244, 17
	s_nop 1
	v_lshl_add_u64 v[4:5], v[174:175], 0, s[0:1]
	v_readlane_b32 s0, v244, 18
	v_readlane_b32 s1, v244, 19
	global_load_dwordx4 v[50:53], v[2:3], off nt
	global_load_dwordx4 v[22:25], v[4:5], off nt
	v_lshl_add_u64 v[2:3], v[174:175], 0, s[0:1]
	v_readlane_b32 s0, v244, 20
	v_readlane_b32 s1, v244, 21
	s_nop 1
	v_lshl_add_u64 v[4:5], v[174:175], 0, s[0:1]
	v_readlane_b32 s0, v244, 22
	v_readlane_b32 s1, v244, 23
	global_load_dwordx4 v[46:49], v[2:3], off nt
	global_load_dwordx4 v[18:21], v[4:5], off nt
	v_lshl_add_u64 v[2:3], v[174:175], 0, s[0:1]
	v_readlane_b32 s0, v244, 24
	v_readlane_b32 s1, v244, 25
	s_nop 1
	v_lshl_add_u64 v[4:5], v[174:175], 0, s[0:1]
	v_readlane_b32 s0, v244, 26
	v_readlane_b32 s1, v244, 27
	global_load_dwordx4 v[38:41], v[2:3], off nt
	global_load_dwordx4 v[14:17], v[4:5], off nt
	v_lshl_add_u64 v[2:3], v[174:175], 0, s[0:1]
	v_readlane_b32 s0, v244, 28
	v_readlane_b32 s1, v244, 29
	s_nop 1
	v_lshl_add_u64 v[4:5], v[174:175], 0, s[0:1]
	v_readlane_b32 s0, v244, 30
	v_readlane_b32 s1, v244, 31
	global_load_dwordx4 v[30:33], v[2:3], off nt
	global_load_dwordx4 v[10:13], v[4:5], off nt
	v_lshl_add_u64 v[2:3], v[174:175], 0, s[0:1]
	v_readlane_b32 s0, v244, 32
	v_readlane_b32 s1, v244, 33
	s_nop 1
	v_lshl_add_u64 v[4:5], v[174:175], 0, s[0:1]
	global_load_dwordx4 v[6:9], v[2:3], off nt
	s_nop 0
	global_load_dwordx4 v[2:5], v[4:5], off nt
	s_waitcnt vmcnt(31)
	v_mul_f32_e32 v107, v107, v65
	v_mul_f32_e32 v109, v109, v67
	v_fmac_f32_e32 v107, v106, v64
	v_fmac_f32_e32 v109, v108, v66
	v_add_f32_e32 v106, v107, v109
	s_waitcnt vmcnt(30)
	v_mul_f32_e32 v111, v111, v65
	v_fmac_f32_e32 v111, v110, v64
	v_mul_f32_e32 v110, v113, v67
	v_fmac_f32_e32 v110, v112, v66
	v_add_f32_e32 v110, v111, v110
	s_waitcnt vmcnt(29)
	v_mul_f32_e32 v115, v115, v65
	v_fmac_f32_e32 v115, v114, v64
	v_mul_f32_e32 v114, v117, v67
	v_fmac_f32_e32 v114, v116, v66
	v_add_f32_e32 v114, v115, v114
	s_waitcnt vmcnt(28)
	v_mul_f32_e32 v119, v119, v65
	v_fmac_f32_e32 v119, v118, v64
	v_mul_f32_e32 v118, v121, v67
	v_fmac_f32_e32 v118, v120, v66
	v_add_f32_e32 v118, v119, v118
	s_waitcnt vmcnt(27)
	v_mul_f32_e32 v123, v123, v65
	v_fmac_f32_e32 v123, v122, v64
	v_mul_f32_e32 v122, v125, v67
	v_fmac_f32_e32 v122, v124, v66
	v_add_f32_e32 v122, v123, v122
	s_waitcnt vmcnt(26)
	v_mul_f32_e32 v127, v127, v65
	v_fmac_f32_e32 v127, v126, v64
	v_mul_f32_e32 v126, v129, v67
	v_fmac_f32_e32 v126, v128, v66
	v_add_f32_e32 v126, v127, v126
	s_waitcnt vmcnt(25)
	v_mul_f32_e32 v131, v131, v65
	v_fmac_f32_e32 v131, v130, v64
	v_mul_f32_e32 v130, v133, v67
	v_fmac_f32_e32 v130, v132, v66
	v_add_f32_e32 v130, v131, v130
	s_waitcnt vmcnt(24)
	v_mul_f32_e32 v135, v135, v65
	v_fmac_f32_e32 v135, v134, v64
	v_mul_f32_e32 v134, v137, v67
	v_fmac_f32_e32 v134, v136, v66
	v_add_f32_e32 v134, v135, v134
	s_waitcnt vmcnt(23)
	v_mul_f32_e32 v139, v139, v65
	v_fmac_f32_e32 v139, v138, v64
	v_mul_f32_e32 v138, v141, v67
	v_fmac_f32_e32 v138, v140, v66
	v_add_f32_e32 v138, v139, v138
	s_waitcnt vmcnt(22)
	v_mul_f32_e32 v143, v143, v65
	v_fmac_f32_e32 v143, v142, v64
	v_mul_f32_e32 v142, v145, v67
	v_fmac_f32_e32 v142, v144, v66
	v_add_f32_e32 v142, v143, v142
	s_waitcnt vmcnt(21)
	v_mul_f32_e32 v147, v147, v65
	v_fmac_f32_e32 v147, v146, v64
	v_mul_f32_e32 v146, v149, v67
	v_fmac_f32_e32 v146, v148, v66
	v_add_f32_e32 v146, v147, v146
	s_waitcnt vmcnt(20)
	v_mul_f32_e32 v151, v151, v65
	v_fmac_f32_e32 v151, v150, v64
	v_mul_f32_e32 v150, v153, v67
	v_fmac_f32_e32 v150, v152, v66
	v_add_f32_e32 v150, v151, v150
	s_waitcnt vmcnt(19)
	v_mul_f32_e32 v155, v155, v65
	v_fmac_f32_e32 v155, v154, v64
	v_mul_f32_e32 v154, v157, v67
	v_fmac_f32_e32 v154, v156, v66
	v_add_f32_e32 v154, v155, v154
	s_waitcnt vmcnt(18)
	v_mul_f32_e32 v159, v159, v65
	v_fmac_f32_e32 v159, v158, v64
	v_mul_f32_e32 v158, v161, v67
	v_fmac_f32_e32 v158, v160, v66
	v_add_f32_e32 v158, v159, v158
	s_waitcnt vmcnt(17)
	v_mul_f32_e32 v163, v163, v65
	v_fmac_f32_e32 v163, v162, v64
	v_mul_f32_e32 v162, v165, v67
	v_fmac_f32_e32 v162, v164, v66
	v_add_f32_e32 v162, v163, v162
	s_waitcnt vmcnt(16)
	v_mul_f32_e32 v167, v167, v65
	v_fmac_f32_e32 v167, v166, v64
	v_mul_f32_e32 v166, v169, v67
	v_fmac_f32_e32 v166, v168, v66
	v_add_f32_e32 v166, v167, v166
	ds_bpermute_b32 v107, v200, v106
	ds_bpermute_b32 v111, v200, v110
	ds_bpermute_b32 v115, v200, v114
	ds_bpermute_b32 v119, v200, v118
	ds_bpermute_b32 v123, v200, v122
	ds_bpermute_b32 v127, v200, v126
	ds_bpermute_b32 v131, v200, v130
	ds_bpermute_b32 v135, v200, v134
	s_waitcnt lgkmcnt(7)
	v_add_f32_e32 v106, v106, v107
	s_waitcnt lgkmcnt(6)
	v_add_f32_e32 v110, v110, v111
	s_waitcnt lgkmcnt(5)
	v_add_f32_e32 v114, v114, v115
	s_waitcnt lgkmcnt(4)
	v_add_f32_e32 v118, v118, v119
	s_waitcnt lgkmcnt(3)
	v_add_f32_e32 v122, v122, v123
	s_waitcnt lgkmcnt(2)
	v_add_f32_e32 v126, v126, v127
	s_waitcnt lgkmcnt(1)
	v_add_f32_e32 v130, v130, v131
	s_waitcnt lgkmcnt(0)
	v_add_f32_e32 v134, v134, v135
	ds_bpermute_b32 v107, v201, v106
	ds_bpermute_b32 v111, v201, v110
	ds_bpermute_b32 v115, v201, v114
	ds_bpermute_b32 v119, v201, v118
	ds_bpermute_b32 v123, v201, v122
	ds_bpermute_b32 v127, v201, v126
	ds_bpermute_b32 v131, v201, v130
	ds_bpermute_b32 v135, v201, v134
	s_waitcnt lgkmcnt(7)
	v_add_f32_e32 v106, v106, v107
	s_waitcnt lgkmcnt(6)
	v_add_f32_e32 v110, v110, v111
	s_waitcnt lgkmcnt(5)
	v_add_f32_e32 v114, v114, v115
	s_waitcnt lgkmcnt(4)
	v_add_f32_e32 v118, v118, v119
	s_waitcnt lgkmcnt(3)
	v_add_f32_e32 v122, v122, v123
	s_waitcnt lgkmcnt(2)
	v_add_f32_e32 v126, v126, v127
	s_waitcnt lgkmcnt(1)
	v_add_f32_e32 v130, v130, v131
	s_waitcnt lgkmcnt(0)
	v_add_f32_e32 v134, v134, v135
	ds_bpermute_b32 v107, v202, v106
	ds_bpermute_b32 v111, v202, v110
	ds_bpermute_b32 v115, v202, v114
	ds_bpermute_b32 v119, v202, v118
	ds_bpermute_b32 v123, v202, v122
	ds_bpermute_b32 v127, v202, v126
	ds_bpermute_b32 v131, v202, v130
	ds_bpermute_b32 v135, v202, v134
	s_waitcnt lgkmcnt(7)
	v_add_f32_e32 v106, v106, v107
	s_waitcnt lgkmcnt(6)
	v_add_f32_e32 v110, v110, v111
	s_waitcnt lgkmcnt(5)
	v_add_f32_e32 v114, v114, v115
	s_waitcnt lgkmcnt(4)
	v_add_f32_e32 v118, v118, v119
	s_waitcnt lgkmcnt(3)
	v_add_f32_e32 v122, v122, v123
	s_waitcnt lgkmcnt(2)
	v_add_f32_e32 v126, v126, v127
	s_waitcnt lgkmcnt(1)
	v_add_f32_e32 v130, v130, v131
	s_waitcnt lgkmcnt(0)
	v_add_f32_e32 v134, v134, v135
	ds_bpermute_b32 v107, v203, v106
	ds_bpermute_b32 v111, v203, v110
	ds_bpermute_b32 v115, v203, v114
	ds_bpermute_b32 v119, v203, v118
	ds_bpermute_b32 v123, v203, v122
	ds_bpermute_b32 v127, v203, v126
	ds_bpermute_b32 v131, v203, v130
	ds_bpermute_b32 v135, v203, v134
	s_waitcnt lgkmcnt(7)
	v_add_f32_e32 v106, v106, v107
	s_waitcnt lgkmcnt(6)
	v_add_f32_e32 v110, v110, v111
	s_waitcnt lgkmcnt(5)
	v_add_f32_e32 v114, v114, v115
	s_waitcnt lgkmcnt(4)
	v_add_f32_e32 v118, v118, v119
	s_waitcnt lgkmcnt(3)
	v_add_f32_e32 v122, v122, v123
	s_waitcnt lgkmcnt(2)
	v_add_f32_e32 v126, v126, v127
	s_waitcnt lgkmcnt(1)
	v_add_f32_e32 v130, v130, v131
	s_waitcnt lgkmcnt(0)
	v_add_f32_e32 v134, v134, v135
	ds_bpermute_b32 v107, v204, v106
	ds_bpermute_b32 v111, v204, v110
	ds_bpermute_b32 v115, v204, v114
	ds_bpermute_b32 v119, v204, v118
	ds_bpermute_b32 v123, v204, v122
	ds_bpermute_b32 v127, v204, v126
	ds_bpermute_b32 v131, v204, v130
	ds_bpermute_b32 v135, v204, v134
	s_waitcnt lgkmcnt(7)
	v_add_f32_e32 v106, v106, v107
	s_waitcnt lgkmcnt(6)
	v_add_f32_e32 v110, v110, v111
	s_waitcnt lgkmcnt(5)
	v_add_f32_e32 v114, v114, v115
	s_waitcnt lgkmcnt(4)
	v_add_f32_e32 v118, v118, v119
	s_waitcnt lgkmcnt(3)
	v_add_f32_e32 v122, v122, v123
	s_waitcnt lgkmcnt(2)
	v_add_f32_e32 v126, v126, v127
	s_waitcnt lgkmcnt(1)
	v_add_f32_e32 v130, v130, v131
	s_waitcnt lgkmcnt(0)
	v_add_f32_e32 v134, v134, v135
	ds_bpermute_b32 v107, v205, v106
	ds_bpermute_b32 v111, v205, v110
	ds_bpermute_b32 v115, v205, v114
	ds_bpermute_b32 v119, v205, v118
	ds_bpermute_b32 v123, v205, v122
	ds_bpermute_b32 v127, v205, v126
	ds_bpermute_b32 v131, v205, v130
	ds_bpermute_b32 v135, v205, v134
	s_waitcnt lgkmcnt(7)
	v_add_f32_e32 v106, v106, v107
	s_waitcnt lgkmcnt(6)
	v_add_f32_e32 v110, v110, v111
	s_waitcnt lgkmcnt(5)
	v_add_f32_e32 v114, v114, v115
	s_waitcnt lgkmcnt(4)
	v_add_f32_e32 v118, v118, v119
	s_waitcnt lgkmcnt(3)
	v_add_f32_e32 v122, v122, v123
	s_waitcnt lgkmcnt(2)
	v_add_f32_e32 v126, v126, v127
	s_waitcnt lgkmcnt(1)
	v_add_f32_e32 v130, v130, v131
	s_waitcnt lgkmcnt(0)
	v_add_f32_e32 v134, v134, v135
	ds_bpermute_b32 v139, v200, v138
	ds_bpermute_b32 v143, v200, v142
	ds_bpermute_b32 v147, v200, v146
	ds_bpermute_b32 v151, v200, v150
	ds_bpermute_b32 v155, v200, v154
	ds_bpermute_b32 v159, v200, v158
	ds_bpermute_b32 v163, v200, v162
	ds_bpermute_b32 v167, v200, v166
	s_waitcnt lgkmcnt(7)
	v_add_f32_e32 v138, v138, v139
	s_waitcnt lgkmcnt(6)
	v_add_f32_e32 v142, v142, v143
	s_waitcnt lgkmcnt(5)
	v_add_f32_e32 v146, v146, v147
	s_waitcnt lgkmcnt(4)
	v_add_f32_e32 v150, v150, v151
	s_waitcnt lgkmcnt(3)
	v_add_f32_e32 v154, v154, v155
	s_waitcnt lgkmcnt(2)
	v_add_f32_e32 v158, v158, v159
	s_waitcnt lgkmcnt(1)
	v_add_f32_e32 v162, v162, v163
	s_waitcnt lgkmcnt(0)
	v_add_f32_e32 v166, v166, v167
	ds_bpermute_b32 v139, v201, v138
	ds_bpermute_b32 v143, v201, v142
	ds_bpermute_b32 v147, v201, v146
	ds_bpermute_b32 v151, v201, v150
	ds_bpermute_b32 v155, v201, v154
	ds_bpermute_b32 v159, v201, v158
	ds_bpermute_b32 v163, v201, v162
	ds_bpermute_b32 v167, v201, v166
	s_waitcnt lgkmcnt(7)
	v_add_f32_e32 v138, v138, v139
	s_waitcnt lgkmcnt(6)
	v_add_f32_e32 v142, v142, v143
	s_waitcnt lgkmcnt(5)
	v_add_f32_e32 v146, v146, v147
	s_waitcnt lgkmcnt(4)
	v_add_f32_e32 v150, v150, v151
	s_waitcnt lgkmcnt(3)
	v_add_f32_e32 v154, v154, v155
	s_waitcnt lgkmcnt(2)
	v_add_f32_e32 v158, v158, v159
	s_waitcnt lgkmcnt(1)
	v_add_f32_e32 v162, v162, v163
	s_waitcnt lgkmcnt(0)
	v_add_f32_e32 v166, v166, v167
	ds_bpermute_b32 v139, v202, v138
	ds_bpermute_b32 v143, v202, v142
	ds_bpermute_b32 v147, v202, v146
	ds_bpermute_b32 v151, v202, v150
	ds_bpermute_b32 v155, v202, v154
	ds_bpermute_b32 v159, v202, v158
	ds_bpermute_b32 v163, v202, v162
	ds_bpermute_b32 v167, v202, v166
	s_waitcnt lgkmcnt(7)
	v_add_f32_e32 v138, v138, v139
	s_waitcnt lgkmcnt(6)
	v_add_f32_e32 v142, v142, v143
	s_waitcnt lgkmcnt(5)
	v_add_f32_e32 v146, v146, v147
	s_waitcnt lgkmcnt(4)
	v_add_f32_e32 v150, v150, v151
	s_waitcnt lgkmcnt(3)
	v_add_f32_e32 v154, v154, v155
	s_waitcnt lgkmcnt(2)
	v_add_f32_e32 v158, v158, v159
	s_waitcnt lgkmcnt(1)
	v_add_f32_e32 v162, v162, v163
	s_waitcnt lgkmcnt(0)
	v_add_f32_e32 v166, v166, v167
	ds_bpermute_b32 v139, v203, v138
	ds_bpermute_b32 v143, v203, v142
	ds_bpermute_b32 v147, v203, v146
	ds_bpermute_b32 v151, v203, v150
	ds_bpermute_b32 v155, v203, v154
	ds_bpermute_b32 v159, v203, v158
	ds_bpermute_b32 v163, v203, v162
	ds_bpermute_b32 v167, v203, v166
	s_waitcnt lgkmcnt(7)
	v_add_f32_e32 v138, v138, v139
	s_waitcnt lgkmcnt(6)
	v_add_f32_e32 v142, v142, v143
	s_waitcnt lgkmcnt(5)
	v_add_f32_e32 v146, v146, v147
	s_waitcnt lgkmcnt(4)
	v_add_f32_e32 v150, v150, v151
	s_waitcnt lgkmcnt(3)
	v_add_f32_e32 v154, v154, v155
	s_waitcnt lgkmcnt(2)
	v_add_f32_e32 v158, v158, v159
	s_waitcnt lgkmcnt(1)
	v_add_f32_e32 v162, v162, v163
	s_waitcnt lgkmcnt(0)
	v_add_f32_e32 v166, v166, v167
	ds_bpermute_b32 v139, v204, v138
	ds_bpermute_b32 v143, v204, v142
	ds_bpermute_b32 v147, v204, v146
	ds_bpermute_b32 v151, v204, v150
	ds_bpermute_b32 v155, v204, v154
	ds_bpermute_b32 v159, v204, v158
	ds_bpermute_b32 v163, v204, v162
	ds_bpermute_b32 v167, v204, v166
	s_waitcnt lgkmcnt(7)
	v_add_f32_e32 v138, v138, v139
	s_waitcnt lgkmcnt(6)
	v_add_f32_e32 v142, v142, v143
	s_waitcnt lgkmcnt(5)
	v_add_f32_e32 v146, v146, v147
	s_waitcnt lgkmcnt(4)
	v_add_f32_e32 v150, v150, v151
	s_waitcnt lgkmcnt(3)
	v_add_f32_e32 v154, v154, v155
	s_waitcnt lgkmcnt(2)
	v_add_f32_e32 v158, v158, v159
	s_waitcnt lgkmcnt(1)
	v_add_f32_e32 v162, v162, v163
	s_waitcnt lgkmcnt(0)
	v_add_f32_e32 v166, v166, v167
	ds_bpermute_b32 v139, v205, v138
	ds_bpermute_b32 v143, v205, v142
	ds_bpermute_b32 v147, v205, v146
	ds_bpermute_b32 v151, v205, v150
	ds_bpermute_b32 v155, v205, v154
	ds_bpermute_b32 v159, v205, v158
	ds_bpermute_b32 v163, v205, v162
	ds_bpermute_b32 v167, v205, v166
	s_waitcnt lgkmcnt(7)
	v_add_f32_e32 v138, v138, v139
	s_waitcnt lgkmcnt(6)
	v_add_f32_e32 v142, v142, v143
	s_waitcnt lgkmcnt(5)
	v_add_f32_e32 v146, v146, v147
	s_waitcnt lgkmcnt(4)
	v_add_f32_e32 v150, v150, v151
	s_waitcnt lgkmcnt(3)
	v_add_f32_e32 v154, v154, v155
	s_waitcnt lgkmcnt(2)
	v_add_f32_e32 v158, v158, v159
	s_waitcnt lgkmcnt(1)
	v_add_f32_e32 v162, v162, v163
	s_waitcnt lgkmcnt(0)
	v_add_f32_e32 v166, v166, v167
	s_movk_i32 s60, 0x40
	s_add_i32 s0, s84, s60
	v_mov_b32_e32 v107, s0
	s_and_saveexec_b64 vcc, s[14:15]
	ds_write_b32 v107, v106
	s_or_b64 exec, exec, vcc
	s_and_saveexec_b64 vcc, s[16:17]
	ds_write_b32 v107, v110 offset:4
	s_or_b64 exec, exec, vcc
	s_and_saveexec_b64 vcc, s[18:19]
	ds_write_b32 v107, v114 offset:8
	s_or_b64 exec, exec, vcc
	s_and_saveexec_b64 vcc, s[20:21]
	ds_write_b32 v107, v118 offset:12
	s_or_b64 exec, exec, vcc
	s_and_saveexec_b64 vcc, s[22:23]
	ds_write_b32 v107, v122 offset:16
	s_or_b64 exec, exec, vcc
	s_and_saveexec_b64 vcc, s[24:25]
	ds_write_b32 v107, v126 offset:20
	s_or_b64 exec, exec, vcc
	s_and_saveexec_b64 vcc, s[26:27]
	ds_write_b32 v107, v130 offset:24
	s_or_b64 exec, exec, vcc
	s_and_saveexec_b64 vcc, s[28:29]
	ds_write_b32 v107, v134 offset:28
	s_or_b64 exec, exec, vcc
	s_and_saveexec_b64 vcc, s[30:31]
	ds_write_b32 v107, v138 offset:32
	s_or_b64 exec, exec, vcc
	s_and_saveexec_b64 vcc, s[34:35]
	ds_write_b32 v107, v142 offset:36
	s_or_b64 exec, exec, vcc
	s_and_saveexec_b64 vcc, s[36:37]
	ds_write_b32 v107, v146 offset:40
	s_or_b64 exec, exec, vcc
	s_and_saveexec_b64 vcc, s[38:39]
	ds_write_b32 v107, v150 offset:44
	s_or_b64 exec, exec, vcc
	s_and_saveexec_b64 vcc, s[40:41]
	ds_write_b32 v107, v154 offset:48
	s_or_b64 exec, exec, vcc
	s_and_saveexec_b64 vcc, s[42:43]
	ds_write_b32 v107, v158 offset:52
	s_or_b64 exec, exec, vcc
	s_and_saveexec_b64 vcc, s[44:45]
	ds_write_b32 v107, v162 offset:56
	s_or_b64 exec, exec, vcc
	s_and_saveexec_b64 vcc, s[46:47]
	ds_write_b32 v107, v166 offset:60
	s_or_b64 exec, exec, vcc
	v_mov_b32_e32 v105, s84
	s_waitcnt lgkmcnt(0)
	s_barrier
	ds_read2st64_b32 v[68:69], v0 offset1:1
	ds_read2st64_b32 v[70:71], v0 offset0:2 offset1:3
	s_waitcnt lgkmcnt(1)
	v_max3_f32 v72, v68, s72, v69
	s_waitcnt lgkmcnt(0)
	v_max3_f32 v72, v72, v70, v71
	ds_bpermute_b32 v73, v200, v72
	s_waitcnt lgkmcnt(0)
	v_max_f32_e32 v73, v73, v73
	v_max_f32_e32 v72, v72, v73
	ds_bpermute_b32 v73, v201, v72
	s_waitcnt lgkmcnt(0)
	v_max_f32_e32 v73, v73, v73
	v_max_f32_e32 v72, v72, v73
	ds_bpermute_b32 v73, v202, v72
	s_waitcnt lgkmcnt(0)
	v_max_f32_e32 v73, v73, v73
	v_max_f32_e32 v72, v72, v73
	ds_bpermute_b32 v73, v203, v72
	s_waitcnt lgkmcnt(0)
	v_max_f32_e32 v73, v73, v73
	v_max_f32_e32 v72, v72, v73
	ds_bpermute_b32 v73, v204, v72
	s_waitcnt lgkmcnt(0)
	v_max_f32_e32 v73, v73, v73
	v_max_f32_e32 v72, v72, v73
	ds_bpermute_b32 v73, v205, v72
	s_waitcnt lgkmcnt(0)
	v_max_f32_e32 v73, v73, v73
	v_max_f32_e32 v104, v72, v73
	v_sub_f32_e32 v68, v68, v104
	v_mul_f32_e32 v68, 0x3fb8aa3b, v68
	v_sub_f32_e32 v69, v69, v104
	v_exp_f32_e32 v68, v68
	v_mul_f32_e32 v69, 0x3fb8aa3b, v69
	v_sub_f32_e32 v70, v70, v104
	v_exp_f32_e32 v69, v69
	v_mul_f32_e32 v70, 0x3fb8aa3b, v70
	v_sub_f32_e32 v71, v71, v104
	v_exp_f32_e32 v70, v70
	v_mul_f32_e32 v71, 0x3fb8aa3b, v71
	v_exp_f32_e32 v71, v71
	v_add_f32_e32 v68, 0, v68
	v_add_f32_e32 v68, v69, v68
	v_add_f32_e32 v68, v70, v68
	v_add_f32_e32 v68, v71, v68
	ds_bpermute_b32 v69, v200, v68
	s_waitcnt lgkmcnt(0)
	v_add_f32_e32 v68, v68, v69
	ds_bpermute_b32 v69, v201, v68
	s_waitcnt lgkmcnt(0)
	v_add_f32_e32 v68, v68, v69
	ds_bpermute_b32 v69, v202, v68
	s_waitcnt lgkmcnt(0)
	v_add_f32_e32 v68, v68, v69
	ds_bpermute_b32 v69, v203, v68
	s_waitcnt lgkmcnt(0)
	v_add_f32_e32 v76, v68, v69
	ds_bpermute_b32 v77, v204, v76
	ds_read_b128 v[68:71], v105
	ds_read_b128 v[72:75], v105 offset:16
	s_waitcnt lgkmcnt(2)
	v_add_f32_e32 v84, v76, v77
	ds_bpermute_b32 v85, v205, v84
	s_waitcnt lgkmcnt(2)
	v_sub_f32_e32 v68, v68, v104
	v_mul_f32_e32 v68, 0x3fb8aa3b, v68
	v_exp_f32_e32 v68, v68
	ds_read_b128 v[76:79], v105 offset:32
	ds_read_b128 v[80:83], v105 offset:48
	s_waitcnt lgkmcnt(2)
	v_add_f32_e32 v84, v84, v85
	v_div_scale_f32 v85, s[0:1], v84, v84, 1.0
	v_rcp_f32_e32 v86, v85
	v_div_scale_f32 v87, vcc, 1.0, v84, 1.0
	v_readlane_b32 s0, v244, 34
	v_fma_f32 v88, -v85, v86, 1.0
	v_fmac_f32_e32 v86, v88, v86
	v_mul_f32_e32 v88, v87, v86
	v_fma_f32 v89, -v85, v88, v87
	v_fmac_f32_e32 v88, v89, v86
	v_fma_f32 v85, -v85, v88, v87
	v_div_fmas_f32 v85, v85, v86, v88
	v_div_fixup_f32 v139, v85, v84, 1.0
	v_mul_f32_e32 v138, v68, v139
	v_sub_f32_e32 v68, v69, v104
	v_sub_f32_e32 v69, v70, v104
	v_mul_f32_e32 v68, 0x3fb8aa3b, v68
	v_mul_f32_e32 v69, 0x3fb8aa3b, v69
	v_sub_f32_e32 v70, v71, v104
	v_exp_f32_e32 v68, v68
	v_exp_f32_e32 v69, v69
	v_mul_f32_e32 v70, 0x3fb8aa3b, v70
	v_exp_f32_e32 v70, v70
	v_sub_f32_e32 v71, v72, v104
	v_mul_f32_e32 v71, 0x3fb8aa3b, v71
	v_mul_f32_e32 v140, v68, v139
	v_mul_f32_e32 v142, v69, v139
	v_sub_f32_e32 v68, v73, v104
	v_sub_f32_e32 v69, v74, v104
	v_exp_f32_e32 v71, v71
	v_mul_f32_e32 v144, v70, v139
	v_mul_f32_e32 v68, 0x3fb8aa3b, v68
	v_mul_f32_e32 v69, 0x3fb8aa3b, v69
	v_sub_f32_e32 v70, v75, v104
	v_exp_f32_e32 v68, v68
	v_exp_f32_e32 v69, v69
	v_mul_f32_e32 v70, 0x3fb8aa3b, v70
	v_exp_f32_e32 v70, v70
	v_mul_f32_e32 v146, v71, v139
	s_waitcnt lgkmcnt(1)
	v_sub_f32_e32 v71, v76, v104
	v_mul_f32_e32 v71, 0x3fb8aa3b, v71
	v_mul_f32_e32 v148, v68, v139
	v_mul_f32_e32 v150, v139, v69
	v_sub_f32_e32 v68, v77, v104
	v_sub_f32_e32 v69, v78, v104
	v_exp_f32_e32 v71, v71
	v_mul_f32_e32 v152, v139, v70
	v_mul_f32_e32 v68, 0x3fb8aa3b, v68
	v_mul_f32_e32 v69, 0x3fb8aa3b, v69
	v_sub_f32_e32 v70, v79, v104
	v_exp_f32_e32 v68, v68
	v_exp_f32_e32 v69, v69
	v_mul_f32_e32 v70, 0x3fb8aa3b, v70
	v_exp_f32_e32 v70, v70
	v_mul_f32_e32 v154, v139, v71
	s_waitcnt lgkmcnt(0)
	v_sub_f32_e32 v71, v80, v104
	v_readlane_b32 s1, v244, 35
	v_mul_f32_e32 v71, 0x3fb8aa3b, v71
	v_mul_f32_e32 v156, v139, v68
	v_mul_f32_e32 v158, v139, v69
	v_lshl_add_u64 v[68:69], v[174:175], 0, s[0:1]
	v_exp_f32_e32 v71, v71
	v_mul_f32_e32 v160, v139, v70
	v_sub_f32_e32 v70, v81, v104
	global_load_dwordx4 v[106:109], v[68:69], off nt
	v_mul_f32_e32 v68, 0x3fb8aa3b, v70
	v_exp_f32_e32 v70, v68
	v_sub_f32_e32 v68, v82, v104
	v_mul_f32_e32 v68, 0x3fb8aa3b, v68
	v_readlane_b32 s0, v244, 36
	v_mul_f32_e32 v162, v139, v71
	v_exp_f32_e32 v71, v68
	v_sub_f32_e32 v68, v83, v104
	v_readlane_b32 s1, v244, 37
	v_mul_f32_e32 v72, 0x3fb8aa3b, v68
	v_mul_f32_e32 v164, v139, v70
	v_lshl_add_u64 v[68:69], v[174:175], 0, s[0:1]
	v_readlane_b32 s0, v244, 38
	v_readlane_b32 s1, v244, 39
	global_load_dwordx4 v[110:113], v[68:69], off nt
	v_mul_f32_e32 v166, v139, v71
	v_lshl_add_u64 v[68:69], v[174:175], 0, s[0:1]
	global_load_dwordx4 v[114:117], v[68:69], off nt
	v_readlane_b32 s0, v244, 40
	v_readlane_b32 s1, v244, 41
	v_exp_f32_e32 v72, v72
	s_waitcnt vmcnt(18)
	v_pk_fma_f32 v[170:171], v[170:171], v[138:139], 0 op_sel_hi:[1,0,0]
	v_lshl_add_u64 v[68:69], v[174:175], 0, s[0:1]
	v_readlane_b32 s0, v244, 42
	v_readlane_b32 s1, v244, 43
	global_load_dwordx4 v[118:121], v[68:69], off nt
	v_mul_f32_e32 v168, v139, v72
	v_lshl_add_u64 v[68:69], v[174:175], 0, s[0:1]
	v_readlane_b32 s0, v244, 44
	v_readlane_b32 s1, v244, 45
	v_pk_fma_f32 v[172:173], v[172:173], v[138:139], 0 op_sel_hi:[1,0,0]
	s_waitcnt vmcnt(18)
	v_pk_fma_f32 v[42:43], v[42:43], v[140:141], v[170:171] op_sel_hi:[1,0,1]
	v_lshl_add_u64 v[70:71], v[174:175], 0, s[0:1]
	global_load_dwordx4 v[122:125], v[68:69], off nt
	global_load_dwordx4 v[126:129], v[70:71], off nt
	v_readlane_b32 s0, v244, 46
	v_readlane_b32 s1, v244, 47
	v_pk_fma_f32 v[44:45], v[44:45], v[140:141], v[172:173] op_sel_hi:[1,0,1]
	s_waitcnt vmcnt(19)
	v_pk_fma_f32 v[42:43], v[58:59], v[142:143], v[42:43] op_sel_hi:[1,0,1]
	v_lshl_add_u64 v[68:69], v[174:175], 0, s[0:1]
	v_readlane_b32 s0, v244, 48
	v_readlane_b32 s1, v244, 49
	v_pk_fma_f32 v[44:45], v[60:61], v[142:143], v[44:45] op_sel_hi:[1,0,1]
	s_waitcnt vmcnt(18)
	v_pk_fma_f32 v[34:35], v[34:35], v[144:145], v[42:43] op_sel_hi:[1,0,1]
	v_lshl_add_u64 v[70:71], v[174:175], 0, s[0:1]
	global_load_dwordx4 v[130:133], v[68:69], off nt
	global_load_dwordx4 v[134:137], v[70:71], off nt
	v_readlane_b32 s0, v244, 50
	v_readlane_b32 s1, v244, 51
	v_pk_fma_f32 v[36:37], v[36:37], v[144:145], v[44:45] op_sel_hi:[1,0,1]
	s_waitcnt vmcnt(19)
	v_pk_fma_f32 v[34:35], v[54:55], v[146:147], v[34:35] op_sel_hi:[1,0,1]
	v_lshl_add_u64 v[68:69], v[174:175], 0, s[0:1]
	v_readlane_b32 s0, v244, 52
	v_readlane_b32 s1, v244, 53
	v_pk_fma_f32 v[36:37], v[56:57], v[146:147], v[36:37] op_sel_hi:[1,0,1]
	s_waitcnt vmcnt(18)
	v_pk_fma_f32 v[26:27], v[26:27], v[148:149], v[34:35] op_sel_hi:[1,0,1]
	v_lshl_add_u64 v[70:71], v[174:175], 0, s[0:1]
	v_readlane_b32 s0, v244, 54
	v_readlane_b32 s1, v244, 55
	global_load_dwordx4 v[94:97], v[68:69], off nt
	global_load_dwordx4 v[90:93], v[70:71], off nt
	v_lshl_add_u64 v[68:69], v[174:175], 0, s[0:1]
	v_readlane_b32 s0, v244, 56
	v_readlane_b32 s1, v244, 57
	v_pk_fma_f32 v[28:29], v[28:29], v[148:149], v[36:37] op_sel_hi:[1,0,1]
	s_waitcnt vmcnt(19)
	v_pk_fma_f32 v[26:27], v[50:51], v[150:151], v[26:27] op_sel_hi:[1,0,1]
	v_lshl_add_u64 v[70:71], v[174:175], 0, s[0:1]
	v_readlane_b32 s0, v244, 58
	v_readlane_b32 s1, v244, 59
	global_load_dwordx4 v[86:89], v[68:69], off nt
	global_load_dwordx4 v[82:85], v[70:71], off nt
	v_lshl_add_u64 v[68:69], v[174:175], 0, s[0:1]
	v_readlane_b32 s0, v244, 60
	v_readlane_b32 s1, v244, 61
	v_pk_fma_f32 v[28:29], v[52:53], v[150:151], v[28:29] op_sel_hi:[1,0,1]
	s_waitcnt vmcnt(20)
	v_pk_fma_f32 v[22:23], v[22:23], v[152:153], v[26:27] op_sel_hi:[1,0,1]
	v_lshl_add_u64 v[70:71], v[174:175], 0, s[0:1]
	global_load_dwordx4 v[78:81], v[68:69], off nt
	global_load_dwordx4 v[74:77], v[70:71], off nt
	v_readlane_b32 s0, v244, 62
	v_readlane_b32 s1, v244, 63
	v_pk_fma_f32 v[24:25], v[24:25], v[152:153], v[28:29] op_sel_hi:[1,0,1]
	s_waitcnt vmcnt(21)
	v_pk_fma_f32 v[22:23], v[46:47], v[154:155], v[22:23] op_sel_hi:[1,0,1]
	v_lshl_add_u64 v[68:69], v[174:175], 0, s[0:1]
	v_readlane_b32 s0, v243, 4
	v_readlane_b32 s1, v243, 5
	v_pk_fma_f32 v[24:25], v[48:49], v[154:155], v[24:25] op_sel_hi:[1,0,1]
	s_waitcnt vmcnt(20)
	v_pk_fma_f32 v[18:19], v[18:19], v[156:157], v[22:23] op_sel_hi:[1,0,1]
	v_lshl_add_u64 v[174:175], v[174:175], 0, s[0:1]
	global_load_dwordx4 v[70:73], v[68:69], off nt
	s_nop 0
	global_load_dwordx4 v[66:69], v[174:175], off nt
	v_pk_fma_f32 v[20:21], v[20:21], v[156:157], v[24:25] op_sel_hi:[1,0,1]
	s_waitcnt vmcnt(21)
	v_pk_fma_f32 v[18:19], v[38:39], v[158:159], v[18:19] op_sel_hi:[1,0,1]
	v_pk_fma_f32 v[20:21], v[40:41], v[158:159], v[20:21] op_sel_hi:[1,0,1]
	s_waitcnt vmcnt(20)
	v_pk_fma_f32 v[14:15], v[14:15], v[160:161], v[18:19] op_sel_hi:[1,0,1]
	v_pk_fma_f32 v[16:17], v[16:17], v[160:161], v[20:21] op_sel_hi:[1,0,1]
	s_waitcnt vmcnt(19)
	v_pk_fma_f32 v[18:19], v[30:31], v[162:163], v[14:15] op_sel_hi:[1,0,1]
	v_pk_fma_f32 v[20:21], v[32:33], v[162:163], v[16:17] op_sel_hi:[1,0,1]
	ds_read_b128 v[14:17], v105 offset:64
	s_waitcnt vmcnt(18)
	v_pk_fma_f32 v[10:11], v[10:11], v[164:165], v[18:19] op_sel_hi:[1,0,1]
	v_pk_fma_f32 v[20:21], v[12:13], v[164:165], v[20:21] op_sel_hi:[1,0,1]
	s_waitcnt vmcnt(17)
	v_pk_fma_f32 v[6:7], v[6:7], v[166:167], v[10:11] op_sel_hi:[1,0,1]
	ds_read_b128 v[10:13], v105 offset:80
	s_waitcnt lgkmcnt(1)
	v_sub_f32_e32 v14, v14, v104
	v_mul_f32_e32 v14, 0x3fb8aa3b, v14
	v_exp_f32_e32 v14, v14
	v_pk_fma_f32 v[8:9], v[8:9], v[166:167], v[20:21] op_sel_hi:[1,0,1]
	s_waitcnt vmcnt(16)
	v_pk_fma_f32 v[2:3], v[2:3], v[168:169], v[6:7] op_sel_hi:[1,0,1]
	v_pk_fma_f32 v[4:5], v[4:5], v[168:169], v[8:9] op_sel_hi:[1,0,1]
	v_mul_f32_e32 v6, v139, v14
	s_waitcnt vmcnt(15)
	v_pk_fma_f32 v[2:3], v[106:107], v[6:7], v[2:3] op_sel_hi:[1,0,1]
	v_pk_fma_f32 v[4:5], v[108:109], v[6:7], v[4:5] op_sel_hi:[1,0,1]
	v_sub_f32_e32 v6, v15, v104
	v_mul_f32_e32 v6, 0x3fb8aa3b, v6
	v_sub_f32_e32 v7, v16, v104
	v_exp_f32_e32 v6, v6
	v_mul_f32_e32 v7, 0x3fb8aa3b, v7
	v_exp_f32_e32 v7, v7
	v_mul_f32_e32 v6, v139, v6
	s_waitcnt vmcnt(14)
	v_pk_fma_f32 v[4:5], v[112:113], v[6:7], v[4:5] op_sel_hi:[1,0,1]
	v_pk_fma_f32 v[2:3], v[110:111], v[6:7], v[2:3] op_sel_hi:[1,0,1]
	v_mul_f32_e32 v6, v139, v7
	s_waitcnt vmcnt(13)
	v_pk_fma_f32 v[2:3], v[114:115], v[6:7], v[2:3] op_sel_hi:[1,0,1]
	v_pk_fma_f32 v[4:5], v[116:117], v[6:7], v[4:5] op_sel_hi:[1,0,1]
	v_sub_f32_e32 v6, v17, v104
	v_mul_f32_e32 v6, 0x3fb8aa3b, v6
	s_waitcnt lgkmcnt(0)
	v_sub_f32_e32 v7, v10, v104
	v_exp_f32_e32 v6, v6
	v_mul_f32_e32 v7, 0x3fb8aa3b, v7
	v_exp_f32_e32 v7, v7
	v_mul_f32_e32 v6, v139, v6
	s_waitcnt vmcnt(12)
	v_pk_fma_f32 v[4:5], v[120:121], v[6:7], v[4:5] op_sel_hi:[1,0,1]
	v_pk_fma_f32 v[2:3], v[118:119], v[6:7], v[2:3] op_sel_hi:[1,0,1]
	v_mul_f32_e32 v6, v139, v7
	s_waitcnt vmcnt(11)
	v_pk_fma_f32 v[2:3], v[122:123], v[6:7], v[2:3] op_sel_hi:[1,0,1]
	v_pk_fma_f32 v[4:5], v[124:125], v[6:7], v[4:5] op_sel_hi:[1,0,1]
	v_sub_f32_e32 v6, v11, v104
	v_mul_f32_e32 v6, 0x3fb8aa3b, v6
	v_sub_f32_e32 v7, v12, v104
	v_exp_f32_e32 v6, v6
	v_mul_f32_e32 v7, 0x3fb8aa3b, v7
	v_exp_f32_e32 v7, v7
	v_mul_f32_e32 v6, v139, v6
	s_waitcnt vmcnt(10)
	v_pk_fma_f32 v[4:5], v[128:129], v[6:7], v[4:5] op_sel_hi:[1,0,1]
	v_pk_fma_f32 v[2:3], v[126:127], v[6:7], v[2:3] op_sel_hi:[1,0,1]
	v_mul_f32_e32 v6, v139, v7
	v_sub_f32_e32 v7, v13, v104
	v_mul_f32_e32 v7, 0x3fb8aa3b, v7
	v_exp_f32_e32 v10, v7
	s_waitcnt vmcnt(9)
	v_pk_fma_f32 v[8:9], v[130:131], v[6:7], v[2:3] op_sel_hi:[1,0,1]
	v_pk_fma_f32 v[6:7], v[132:133], v[6:7], v[4:5] op_sel_hi:[1,0,1]
	ds_read_b128 v[2:5], v105 offset:96
	v_mul_f32_e32 v10, v139, v10
	s_waitcnt vmcnt(8)
	v_pk_fma_f32 v[12:13], v[136:137], v[10:11], v[6:7] op_sel_hi:[1,0,1]
	v_pk_fma_f32 v[10:11], v[134:135], v[10:11], v[8:9] op_sel_hi:[1,0,1]
	ds_read_b128 v[6:9], v105 offset:112
	s_waitcnt lgkmcnt(1)
	v_sub_f32_e32 v2, v2, v104
	v_mul_f32_e32 v2, 0x3fb8aa3b, v2
	v_sub_f32_e32 v3, v3, v104
	v_exp_f32_e32 v2, v2
	v_mul_f32_e32 v3, 0x3fb8aa3b, v3
	v_sub_f32_e32 v4, v4, v104
	v_exp_f32_e32 v14, v3
	v_mul_f32_e32 v4, 0x3fb8aa3b, v4
	v_sub_f32_e32 v5, v5, v104
	v_exp_f32_e32 v4, v4
	v_mul_f32_e32 v5, 0x3fb8aa3b, v5
	s_waitcnt lgkmcnt(0)
	v_sub_f32_e32 v6, v6, v104
	v_exp_f32_e32 v5, v5
	v_mul_f32_e32 v6, 0x3fb8aa3b, v6
	v_sub_f32_e32 v7, v7, v104
	v_mul_f32_e32 v2, v139, v2
	v_exp_f32_e32 v6, v6
	v_mul_f32_e32 v7, 0x3fb8aa3b, v7
	s_waitcnt vmcnt(7)
	v_pk_fma_f32 v[10:11], v[94:95], v[2:3], v[10:11] op_sel_hi:[1,0,1]
	v_pk_fma_f32 v[2:3], v[96:97], v[2:3], v[12:13] op_sel_hi:[1,0,1]
	v_mul_f32_e32 v12, v139, v14
	v_exp_f32_e32 v7, v7
	s_waitcnt vmcnt(6)
	v_pk_fma_f32 v[2:3], v[92:93], v[12:13], v[2:3] op_sel_hi:[1,0,1]
	v_pk_fma_f32 v[10:11], v[90:91], v[12:13], v[10:11] op_sel_hi:[1,0,1]
	v_mul_f32_e32 v4, v139, v4
	s_waitcnt vmcnt(5)
	v_pk_fma_f32 v[10:11], v[86:87], v[4:5], v[10:11] op_sel_hi:[1,0,1]
	v_pk_fma_f32 v[2:3], v[88:89], v[4:5], v[2:3] op_sel_hi:[1,0,1]
	v_mul_f32_e32 v4, v139, v5
	s_waitcnt vmcnt(4)
	v_pk_fma_f32 v[2:3], v[84:85], v[4:5], v[2:3] op_sel_hi:[1,0,1]
	v_pk_fma_f32 v[4:5], v[82:83], v[4:5], v[10:11] op_sel_hi:[1,0,1]
	v_mul_f32_e32 v6, v139, v6
	s_waitcnt vmcnt(3)
	v_pk_fma_f32 v[4:5], v[78:79], v[6:7], v[4:5] op_sel_hi:[1,0,1]
	v_pk_fma_f32 v[2:3], v[80:81], v[6:7], v[2:3] op_sel_hi:[1,0,1]
	v_mul_f32_e32 v6, v139, v7
	s_waitcnt vmcnt(2)
	v_pk_fma_f32 v[2:3], v[76:77], v[6:7], v[2:3] op_sel_hi:[1,0,1]
	v_pk_fma_f32 v[4:5], v[74:75], v[6:7], v[4:5] op_sel_hi:[1,0,1]
	v_sub_f32_e32 v6, v8, v104
	v_mul_f32_e32 v6, 0x3fb8aa3b, v6
	v_sub_f32_e32 v7, v9, v104
	v_exp_f32_e32 v6, v6
	v_mul_f32_e32 v7, 0x3fb8aa3b, v7
	v_exp_f32_e32 v7, v7
	v_mul_f32_e32 v6, v139, v6
	s_waitcnt vmcnt(1)
	v_pk_fma_f32 v[8:9], v[70:71], v[6:7], v[4:5] op_sel_hi:[1,0,1]
	v_pk_fma_f32 v[2:3], v[72:73], v[6:7], v[2:3] op_sel_hi:[1,0,1]
	v_mul_f32_e32 v6, v139, v7
	s_waitcnt vmcnt(0)
	v_pk_fma_f32 v[4:5], v[68:69], v[6:7], v[2:3] op_sel_hi:[1,0,1]
	v_pk_fma_f32 v[2:3], v[66:67], v[6:7], v[8:9] op_sel_hi:[1,0,1]
	ds_write_b128 v102, v[2:5] offset:4096
	s_waitcnt lgkmcnt(0)
	s_waitcnt lgkmcnt(0)
	s_barrier
	s_and_saveexec_b64 s[10:11], s[12:13]
	s_cbranch_execz .LBB11_2190
	ds_read2st64_b32 v[2:3], v103 offset0:16 offset1:20
	s_lshl_b64 s[0:1], s[88:89], 1
	s_add_u32 s0, s8, s0
	s_addc_u32 s1, s9, s1
	s_lshl_b32 s48, s68, 1
	s_waitcnt lgkmcnt(0)
	v_add_f32_e32 v2, 0, v2
	v_add_f32_e32 v4, v2, v3
	ds_read2st64_b32 v[2:3], v103 offset0:24 offset1:28
	s_add_u32 s0, s0, s48
	s_addc_u32 s1, s1, 0
	s_waitcnt lgkmcnt(0)
	v_add_f32_e32 v2, v4, v2
	v_add_f32_e32 v4, v2, v3
	ds_read2st64_b32 v[2:3], v103 offset0:32 offset1:36
	s_waitcnt lgkmcnt(0)
	v_add_f32_e32 v2, v4, v2
	v_add_f32_e32 v4, v2, v3
	ds_read2st64_b32 v[2:3], v103 offset0:40 offset1:44
	s_waitcnt lgkmcnt(0)
	v_add_f32_e32 v2, v4, v2
	v_add_f32_e32 v2, v2, v3
	v_cvt_pk_bf16_f32 v4, v2, v1
	v_lshl_add_u64 v[2:3], v[98:99], 1, s[0:1]
	global_store_short v[2:3], v4, off sc1
	s_branch .LBB11_2190
